# FFN-up epilogue stores marked nt (streaming 512 MiB hidden output should not displace A/B panels from L2/MALL) on top of acc-major MFMA order
# speedup vs baseline: 1.0124x; 1.0016x over previous
;     __device__ __forceinline__ size_t a_koff(int t) const { return (size_t)t * 128; }
;     __device__ __forceinline__ size_t a_koff(int t) const { return (size_t)t * 32768; }
; #define PG8_STAGE(bufoff, gbase, voff) do { _Pragma("unroll") for (int _i = 0; _i < 2; ++_i) \
;         __builtin_amdgcn_global_load_lds((const unsigned*)((const char*)(gbase) + (size_t)_i * p##voff + (voff)), (LAS unsigned*)(lds + (bufoff) + ldsw + _i * 8192), 16, 0, 0); } while (0)
; #define PG8_LDA(dst, b, h) do { _Pragma("unroll") for (int m = 0; m < 4; ++m) _Pragma("unroll") for (int k = 0; k < 2; ++k) dst[m][k] = *(const LAS bf16x8*)(lds + PG8_SA(b, h) + aoff + m * 2048 + k * 1024); } while (0)
; #define PG8_LDB(dst, b, h) do { _Pragma("unroll") for (int n = 0; n < 2; ++n) _Pragma("unroll") for (int k = 0; k < 2; ++k) dst[n][k] = *(const LAS bf16x8*)(lds + PG8_SB(b, h) + boff + n * 2048 + k * 1024); } while (0)
; #define PG8_WAIT_V(n) asm volatile("s_waitcnt vmcnt(" #n ")" ::: "memory")
; #define PG8_WAIT_L(n) asm volatile("s_waitcnt lgkmcnt(" #n ")" ::: "memory")
; #define PG8_BAR __builtin_amdgcn_s_barrier()
; #define PG8_SCHED __builtin_amdgcn_sched_barrier(0)
;     __device__ __forceinline__ size_t a_koff(int t) const { return ((size_t)(t >> 1) * 3072 + (size_t)(t & 1) * 64) * 2; }
;     __device__ __forceinline__ size_t a_koff(int t) const { return (size_t)t * 128; }
;     ...
;             const char* a1 = cA + g.a_koff(t + 1);
;             const char* a2 = last ? nA : cA + g.a_koff(t + 2); const char* b2 = last ? nB : cB + (size_t)(t + 2) * kstep;
;             const char* a3 = last ? nA + g.a_koff(1) : cA + g.a_koff(t + 3); const char* b3 = b2 + kstep;
;             PG8_LDB(B0, 0, 0); PG8_LDB(B1, 0, 1); PG8_SCHED; PG8_LDA(At, 0, 0); PG8_STAGE(PG8_SA(1, 1), a1 + hstepA, voffA);
;             PG8_WAIT_V(8); PG8_WAIT_L(0); PG8_BAR; PG8_MMA(0, 0, At, B0); PG8_MMA(0, 1, At, B1); PG8_BAR; PG8_SCHED;
;             PG8_LDA(At, 0, 1); PG8_STAGE(PG8_SB(0, 0), b2, voffB); PG8_STAGE(PG8_SB(0, 1), b2 + hstepB, voffB); PG8_STAGE(PG8_SA(0, 0), a2, voffA);
;             PG8_WAIT_V(8); PG8_WAIT_L(0); PG8_BAR; PG8_MMA(1, 0, At, B0); PG8_MMA(1, 1, At, B1); PG8_BAR; PG8_SCHED;
.LBB0_1206:
	ds_read_b128 v[148:151], v144
	ds_read_b128 v[152:155], v144 offset:1024
	ds_read_b128 v[156:159], v144 offset:2048
	ds_read_b128 v[160:163], v144 offset:3072
	ds_read_b128 v[164:167], v145
	ds_read_b128 v[168:171], v145 offset:1024
	ds_read_b128 v[172:175], v145 offset:2048
	ds_read_b128 v[176:179], v145 offset:3072
	s_add_u32 s46, s42, s44
	s_addc_u32 s47, s43, s45
	s_add_u32 s74, s46, 0x10000
	s_addc_u32 s75, s47, 0
	s_add_u32 s46, s46, 0x18000
	s_addc_u32 s47, s47, 0
	s_cmp_eq_u32 s44, 0x1f0000
	s_cselect_b32 s47, s68, s47
	s_cselect_b32 s46, s67, s46
	s_cselect_b32 s73, s29, s70
	s_cselect_b32 s72, s66, s69
	s_cselect_b32 s75, s35, s75
	s_cselect_b32 s74, s65, s74
	v_lshl_add_u64 v[184:185], v[142:143], 0, s[44:45]
	v_lshl_add_u64 v[216:217], v[184:185], 0, s[76:77]
	s_add_i32 m0, s52, 0xc000
	ds_read_b128 v[180:183], v146
	ds_read_b128 v[188:191], v146 offset:1024
	ds_read_b128 v[192:195], v146 offset:2048
	ds_read_b128 v[196:199], v146 offset:3072
	ds_read_b128 v[200:203], v146 offset:4096
	ds_read_b128 v[204:207], v146 offset:5120
	ds_read_b128 v[208:211], v146 offset:6144
	ds_read_b128 v[212:215], v146 offset:7168
	global_load_lds_dwordx4 v[216:217], off
	v_lshl_add_u64 v[184:185], v[184:185], 0, s[26:27]
	s_add_i32 m0, s52, 0xe000
	s_nop 0
	global_load_lds_dwordx4 v[184:185], off
	s_waitcnt vmcnt(8)
	s_waitcnt lgkmcnt(0)
	s_barrier
	s_setprio 1
	s_waitcnt lgkmcnt(0)
	v_mfma_f32_16x16x32_bf16 v[126:129], v[148:151], v[180:183], v[126:129]
	v_mfma_f32_16x16x32_bf16 v[126:129], v[152:155], v[188:191], v[126:129]
	v_mfma_f32_16x16x32_bf16 v[122:125], v[156:159], v[180:183], v[122:125]
	v_mfma_f32_16x16x32_bf16 v[122:125], v[160:163], v[188:191], v[122:125]
	v_mfma_f32_16x16x32_bf16 v[110:113], v[148:151], v[192:195], v[110:113]
	v_mfma_f32_16x16x32_bf16 v[110:113], v[152:155], v[196:199], v[110:113]
	v_mfma_f32_16x16x32_bf16 v[106:109], v[156:159], v[192:195], v[106:109]
	v_mfma_f32_16x16x32_bf16 v[106:109], v[160:163], v[196:199], v[106:109]
	v_mfma_f32_16x16x32_bf16 v[94:97], v[148:151], v[200:203], v[94:97]
	v_mfma_f32_16x16x32_bf16 v[94:97], v[152:155], v[204:207], v[94:97]
	v_mfma_f32_16x16x32_bf16 v[90:93], v[156:159], v[200:203], v[90:93]
	v_mfma_f32_16x16x32_bf16 v[90:93], v[160:163], v[204:207], v[90:93]
	v_mfma_f32_16x16x32_bf16 v[78:81], v[148:151], v[208:211], v[78:81]
	v_mfma_f32_16x16x32_bf16 v[78:81], v[152:155], v[212:215], v[78:81]
	v_mfma_f32_16x16x32_bf16 v[74:77], v[156:159], v[208:211], v[74:77]
	v_mfma_f32_16x16x32_bf16 v[74:77], v[160:163], v[212:215], v[74:77]
	s_setprio 0
	s_setprio 1
	v_mfma_f32_16x16x32_bf16 v[118:121], v[164:167], v[180:183], v[118:121]
	v_mfma_f32_16x16x32_bf16 v[118:121], v[168:171], v[188:191], v[118:121]
	v_mfma_f32_16x16x32_bf16 v[114:117], v[172:175], v[180:183], v[114:117]
	v_mfma_f32_16x16x32_bf16 v[114:117], v[176:179], v[188:191], v[114:117]
	v_mfma_f32_16x16x32_bf16 v[102:105], v[164:167], v[192:195], v[102:105]
	v_mfma_f32_16x16x32_bf16 v[102:105], v[168:171], v[196:199], v[102:105]
	v_mfma_f32_16x16x32_bf16 v[98:101], v[172:175], v[192:195], v[98:101]
	v_mfma_f32_16x16x32_bf16 v[98:101], v[176:179], v[196:199], v[98:101]
	v_mfma_f32_16x16x32_bf16 v[86:89], v[164:167], v[200:203], v[86:89]
	v_mfma_f32_16x16x32_bf16 v[86:89], v[168:171], v[204:207], v[86:89]
	v_mfma_f32_16x16x32_bf16 v[82:85], v[172:175], v[200:203], v[82:85]
	v_mfma_f32_16x16x32_bf16 v[82:85], v[176:179], v[204:207], v[82:85]
	v_mfma_f32_16x16x32_bf16 v[70:73], v[164:167], v[208:211], v[70:73]
	v_mfma_f32_16x16x32_bf16 v[70:73], v[168:171], v[212:215], v[70:73]
	v_mfma_f32_16x16x32_bf16 v[66:69], v[172:175], v[208:211], v[66:69]
	v_mfma_f32_16x16x32_bf16 v[66:69], v[176:179], v[212:215], v[66:69]
	s_setprio 0
	s_barrier
	v_lshl_add_u64 v[184:185], s[72:73], 0, v[132:133]
	s_add_i32 s72, s63, s50
	s_mov_b32 m0, s72
	ds_read_b128 v[180:183], v146 offset:16384
	ds_read_b128 v[188:191], v146 offset:17408
	ds_read_b128 v[192:195], v146 offset:18432
	ds_read_b128 v[196:199], v146 offset:19456
	ds_read_b128 v[200:203], v146 offset:20480
	ds_read_b128 v[204:207], v146 offset:21504
	ds_read_b128 v[208:211], v146 offset:22528
	ds_read_b128 v[212:215], v146 offset:23552
	global_load_lds_dwordx4 v[184:185], off
	v_lshl_add_u64 v[216:217], v[184:185], 0, s[4:5]
	s_add_i32 m0, s72, 0x2000
	s_add_i32 s72, s64, s50
	global_load_lds_dwordx4 v[216:217], off
	v_lshl_add_u64 v[216:217], v[184:185], 0, s[6:7]
	s_mov_b32 m0, s72
	s_nop 0
	global_load_lds_dwordx4 v[216:217], off
	v_lshl_add_u64 v[216:217], v[184:185], 0, s[8:9]
	s_add_i32 m0, s72, 0x2000
	s_nop 0
	global_load_lds_dwordx4 v[216:217], off
	v_lshl_add_u64 v[216:217], s[74:75], 0, v[130:131]
	s_mov_b32 m0, s52
	v_lshl_add_u64 v[218:219], v[216:217], 0, s[10:11]
	global_load_lds_dwordx4 v[216:217], off
	s_mov_b32 m0, s53
	s_nop 0
	global_load_lds_dwordx4 v[218:219], off
	s_waitcnt vmcnt(8)
	s_waitcnt lgkmcnt(0)
	s_barrier
; #define PG8_STAGE(bufoff, gbase, voff) do { _Pragma("unroll") for (int _i = 0; _i < 2; ++_i) \
;         __builtin_amdgcn_global_load_lds((const unsigned*)((const char*)(gbase) + (size_t)_i * p##voff + (voff)), (LAS unsigned*)(lds + (bufoff) + ldsw + _i * 8192), 16, 0, 0); } while (0)
; #define PG8_LDA(dst, b, h) do { _Pragma("unroll") for (int m = 0; m < 4; ++m) _Pragma("unroll") for (int k = 0; k < 2; ++k) dst[m][k] = *(const LAS bf16x8*)(lds + PG8_SA(b, h) + aoff + m * 2048 + k * 1024); } while (0)
; #define PG8_LDB(dst, b, h) do { _Pragma("unroll") for (int n = 0; n < 2; ++n) _Pragma("unroll") for (int k = 0; k < 2; ++k) dst[n][k] = *(const LAS bf16x8*)(lds + PG8_SB(b, h) + boff + n * 2048 + k * 1024); } while (0)
; #define PG8_WAIT_V(n) asm volatile("s_waitcnt vmcnt(" #n ")" ::: "memory")
; #define PG8_WAIT_L(n) asm volatile("s_waitcnt lgkmcnt(" #n ")" ::: "memory")
; #define PG8_BAR __builtin_amdgcn_s_barrier()
; #define PG8_SCHED __builtin_amdgcn_sched_barrier(0)
;     ...
;             PG8_WAIT_V(8); PG8_WAIT_L(0); PG8_BAR; PG8_MMA(1, 0, At, B0); PG8_MMA(1, 1, At, B1); PG8_BAR; PG8_SCHED;
;             PG8_LDB(B0, 1, 0); PG8_LDB(B1, 1, 1); PG8_SCHED; PG8_LDA(At, 1, 0); PG8_STAGE(PG8_SA(0, 1), a2 + hstepA, voffA);
;             PG8_WAIT_V(8); PG8_WAIT_L(0); PG8_BAR; PG8_MMA(0, 0, At, B0); PG8_MMA(0, 1, At, B1); PG8_BAR; PG8_SCHED;
;             PG8_LDA(At, 1, 1); PG8_STAGE(PG8_SB(1, 0), b3, voffB); PG8_STAGE(PG8_SB(1, 1), b3 + hstepB, voffB); PG8_STAGE(PG8_SA(1, 0), a3, voffA);
;             PG8_WAIT_V(8); PG8_WAIT_L(0); PG8_BAR; PG8_MMA(1, 0, At, B0); PG8_MMA(1, 1, At, B1); PG8_BAR; PG8_SCHED;
	s_setprio 1
	s_waitcnt lgkmcnt(0)
	v_mfma_f32_16x16x32_bf16 v[62:65], v[148:151], v[180:183], v[62:65]
	v_mfma_f32_16x16x32_bf16 v[62:65], v[152:155], v[188:191], v[62:65]
	v_mfma_f32_16x16x32_bf16 v[58:61], v[156:159], v[180:183], v[58:61]
	v_mfma_f32_16x16x32_bf16 v[58:61], v[160:163], v[188:191], v[58:61]
	v_mfma_f32_16x16x32_bf16 v[46:49], v[148:151], v[192:195], v[46:49]
	v_mfma_f32_16x16x32_bf16 v[46:49], v[152:155], v[196:199], v[46:49]
	v_mfma_f32_16x16x32_bf16 v[42:45], v[156:159], v[192:195], v[42:45]
	v_mfma_f32_16x16x32_bf16 v[42:45], v[160:163], v[196:199], v[42:45]
	v_mfma_f32_16x16x32_bf16 v[30:33], v[148:151], v[200:203], v[30:33]
	v_mfma_f32_16x16x32_bf16 v[30:33], v[152:155], v[204:207], v[30:33]
	v_mfma_f32_16x16x32_bf16 v[26:29], v[156:159], v[200:203], v[26:29]
	v_mfma_f32_16x16x32_bf16 v[26:29], v[160:163], v[204:207], v[26:29]
	v_mfma_f32_16x16x32_bf16 v[14:17], v[148:151], v[208:211], v[14:17]
	v_mfma_f32_16x16x32_bf16 v[14:17], v[152:155], v[212:215], v[14:17]
	v_mfma_f32_16x16x32_bf16 v[10:13], v[156:159], v[208:211], v[10:13]
	v_mfma_f32_16x16x32_bf16 v[10:13], v[160:163], v[212:215], v[10:13]
	s_setprio 0
	s_setprio 1
	v_mfma_f32_16x16x32_bf16 v[54:57], v[164:167], v[180:183], v[54:57]
	v_mfma_f32_16x16x32_bf16 v[54:57], v[168:171], v[188:191], v[54:57]
	v_mfma_f32_16x16x32_bf16 v[50:53], v[172:175], v[180:183], v[50:53]
	v_mfma_f32_16x16x32_bf16 v[50:53], v[176:179], v[188:191], v[50:53]
	v_mfma_f32_16x16x32_bf16 v[38:41], v[164:167], v[192:195], v[38:41]
	v_mfma_f32_16x16x32_bf16 v[38:41], v[168:171], v[196:199], v[38:41]
	v_mfma_f32_16x16x32_bf16 v[34:37], v[172:175], v[192:195], v[34:37]
	v_mfma_f32_16x16x32_bf16 v[34:37], v[176:179], v[196:199], v[34:37]
	v_mfma_f32_16x16x32_bf16 v[22:25], v[164:167], v[200:203], v[22:25]
	v_mfma_f32_16x16x32_bf16 v[22:25], v[168:171], v[204:207], v[22:25]
	v_mfma_f32_16x16x32_bf16 v[18:21], v[172:175], v[200:203], v[18:21]
	v_mfma_f32_16x16x32_bf16 v[18:21], v[176:179], v[204:207], v[18:21]
	v_mfma_f32_16x16x32_bf16 v[6:9], v[164:167], v[208:211], v[6:9]
	v_mfma_f32_16x16x32_bf16 v[6:9], v[168:171], v[212:215], v[6:9]
	v_mfma_f32_16x16x32_bf16 v[2:5], v[172:175], v[208:211], v[2:5]
	v_mfma_f32_16x16x32_bf16 v[2:5], v[176:179], v[212:215], v[2:5]
	s_setprio 0
	s_barrier
	s_add_i32 s72, 0, 0x18000
	s_add_i32 s73, 0, 0x1c000
	v_add_u32_e32 v160, s72, v1
	v_add_u32_e32 v176, s73, v1
	ds_read_b128 v[148:151], v160
	ds_read_b128 v[152:155], v160 offset:1024
	ds_read_b128 v[156:159], v160 offset:2048
	ds_read_b128 v[160:163], v160 offset:3072
	ds_read_b128 v[164:167], v176
	ds_read_b128 v[168:171], v176 offset:1024
	ds_read_b128 v[172:175], v176 offset:2048
	ds_read_b128 v[176:179], v176 offset:3072
	s_mov_b32 m0, s54
	v_lshl_add_u64 v[218:219], v[216:217], 0, s[12:13]
	ds_read_b128 v[180:183], v146 offset:32768
	ds_read_b128 v[188:191], v146 offset:33792
	ds_read_b128 v[192:195], v146 offset:34816
	ds_read_b128 v[196:199], v146 offset:35840
	ds_read_b128 v[200:203], v146 offset:36864
	ds_read_b128 v[204:207], v146 offset:37888
	ds_read_b128 v[208:211], v146 offset:38912
	ds_read_b128 v[212:215], v146 offset:39936
	global_load_lds_dwordx4 v[218:219], off
	v_lshl_add_u64 v[216:217], v[216:217], 0, s[14:15]
	s_mov_b32 m0, s55
	s_nop 0
	global_load_lds_dwordx4 v[216:217], off
	s_waitcnt vmcnt(8)
	s_waitcnt lgkmcnt(0)
	s_barrier
	s_setprio 1
	s_waitcnt lgkmcnt(0)
	v_mfma_f32_16x16x32_bf16 v[126:129], v[148:151], v[180:183], v[126:129]
	v_mfma_f32_16x16x32_bf16 v[126:129], v[152:155], v[188:191], v[126:129]
	v_mfma_f32_16x16x32_bf16 v[122:125], v[156:159], v[180:183], v[122:125]
	v_mfma_f32_16x16x32_bf16 v[122:125], v[160:163], v[188:191], v[122:125]
	v_mfma_f32_16x16x32_bf16 v[110:113], v[148:151], v[192:195], v[110:113]
	v_mfma_f32_16x16x32_bf16 v[110:113], v[152:155], v[196:199], v[110:113]
	v_mfma_f32_16x16x32_bf16 v[106:109], v[156:159], v[192:195], v[106:109]
	v_mfma_f32_16x16x32_bf16 v[106:109], v[160:163], v[196:199], v[106:109]
	v_mfma_f32_16x16x32_bf16 v[94:97], v[148:151], v[200:203], v[94:97]
	v_mfma_f32_16x16x32_bf16 v[94:97], v[152:155], v[204:207], v[94:97]
	v_mfma_f32_16x16x32_bf16 v[90:93], v[156:159], v[200:203], v[90:93]
	v_mfma_f32_16x16x32_bf16 v[90:93], v[160:163], v[204:207], v[90:93]
	v_mfma_f32_16x16x32_bf16 v[78:81], v[148:151], v[208:211], v[78:81]
	v_mfma_f32_16x16x32_bf16 v[78:81], v[152:155], v[212:215], v[78:81]
	v_mfma_f32_16x16x32_bf16 v[74:77], v[156:159], v[208:211], v[74:77]
	v_mfma_f32_16x16x32_bf16 v[74:77], v[160:163], v[212:215], v[74:77]
	s_setprio 0
	s_setprio 1
	v_mfma_f32_16x16x32_bf16 v[118:121], v[164:167], v[180:183], v[118:121]
	v_mfma_f32_16x16x32_bf16 v[118:121], v[168:171], v[188:191], v[118:121]
	v_mfma_f32_16x16x32_bf16 v[114:117], v[172:175], v[180:183], v[114:117]
	v_mfma_f32_16x16x32_bf16 v[114:117], v[176:179], v[188:191], v[114:117]
	v_mfma_f32_16x16x32_bf16 v[102:105], v[164:167], v[192:195], v[102:105]
	v_mfma_f32_16x16x32_bf16 v[102:105], v[168:171], v[196:199], v[102:105]
	v_mfma_f32_16x16x32_bf16 v[98:101], v[172:175], v[192:195], v[98:101]
	v_mfma_f32_16x16x32_bf16 v[98:101], v[176:179], v[196:199], v[98:101]
	v_mfma_f32_16x16x32_bf16 v[86:89], v[164:167], v[200:203], v[86:89]
	v_mfma_f32_16x16x32_bf16 v[86:89], v[168:171], v[204:207], v[86:89]
	v_mfma_f32_16x16x32_bf16 v[82:85], v[172:175], v[200:203], v[82:85]
	v_mfma_f32_16x16x32_bf16 v[82:85], v[176:179], v[204:207], v[82:85]
	v_mfma_f32_16x16x32_bf16 v[70:73], v[164:167], v[208:211], v[70:73]
	v_mfma_f32_16x16x32_bf16 v[70:73], v[168:171], v[212:215], v[70:73]
	v_mfma_f32_16x16x32_bf16 v[66:69], v[172:175], v[208:211], v[66:69]
	v_mfma_f32_16x16x32_bf16 v[66:69], v[176:179], v[212:215], v[66:69]
	s_setprio 0
	s_barrier
; __device__ __forceinline__ unsigned cvtpk(float lo, float hi) { f32x2 v = {lo, hi}; bf16x2_t b = __builtin_convertvector(v, bf16x2_t); return __builtin_bit_cast(unsigned, b); }
; #define PG8_STAGE(bufoff, gbase, voff) do { _Pragma("unroll") for (int _i = 0; _i < 2; ++_i) \
;         __builtin_amdgcn_global_load_lds((const unsigned*)((const char*)(gbase) + (size_t)_i * p##voff + (voff)), (LAS unsigned*)(lds + (bufoff) + ldsw + _i * 8192), 16, 0, 0); } while (0)
; #define PG8_LDA(dst, b, h) do { _Pragma("unroll") for (int m = 0; m < 4; ++m) _Pragma("unroll") for (int k = 0; k < 2; ++k) dst[m][k] = *(const LAS bf16x8*)(lds + PG8_SA(b, h) + aoff + m * 2048 + k * 1024); } while (0)
; #define PG8_WAIT_V(n) asm volatile("s_waitcnt vmcnt(" #n ")" ::: "memory")
; #define PG8_WAIT_L(n) asm volatile("s_waitcnt lgkmcnt(" #n ")" ::: "memory")
; #define PG8_BAR __builtin_amdgcn_s_barrier()
; #define PG8_SCHED __builtin_amdgcn_sched_barrier(0)
;     ...
;             PG8_LDA(At, 1, 1); PG8_STAGE(PG8_SB(1, 0), b3, voffB); PG8_STAGE(PG8_SB(1, 1), b3 + hstepB, voffB); PG8_STAGE(PG8_SA(1, 0), a3, voffA);
;             PG8_WAIT_V(8); PG8_WAIT_L(0); PG8_BAR; PG8_MMA(1, 0, At, B0); PG8_MMA(1, 1, At, B1); PG8_BAR; PG8_SCHED;
;     __device__ __forceinline__ void operator()(const Acc& acc, const Unit& u, int wr, int wc, int fr, int fq) const {
;     ...
;             for (int m = 0; m < 4; ++m) { bf16_t* rp = O + (((size_t)u.pm * (DFF / 64) + kt0) * 256 + (rl + ai * 128 + m * 16)) * 64 + cl;
; #pragma unroll
;                 for (int bj = 0; bj < 2; ++bj) { f32x4 v0 = acc[ai][bj][m][0], v1 = acc[ai][bj][m][1];
; #pragma unroll
;                     for (int e = 0; e < 4; ++e) { const float a = fmaxf(v0[e], 0.f), b = fmaxf(v1[e], 0.f); v0[e] = a * a; v1[e] = b * b; }
;                     u32x4 w; w.x = cvtpk(v0[0], v0[1]); w.y = cvtpk(v0[2], v0[3]); w.z = cvtpk(v1[0], v1[1]); w.w = cvtpk(v1[2], v1[3]);
;                     *(u32x4*)(rp + (size_t)bj * 2 * 256 * 64) = w; } }
	s_add_i32 s72, s72, s50
	v_lshl_add_u64 v[216:217], v[184:185], 0, s[18:19]
	s_mov_b32 m0, s72
	ds_read_b128 v[180:183], v146 offset:49152
	ds_read_b128 v[188:191], v146 offset:50176
	ds_read_b128 v[192:195], v146 offset:51200
	ds_read_b128 v[196:199], v146 offset:52224
	ds_read_b128 v[200:203], v146 offset:53248
	ds_read_b128 v[204:207], v146 offset:54272
	ds_read_b128 v[208:211], v146 offset:55296
	ds_read_b128 v[212:215], v146 offset:56320
	global_load_lds_dwordx4 v[216:217], off
	v_lshl_add_u64 v[216:217], v[184:185], 0, s[20:21]
	s_add_i32 m0, s72, 0x2000
	s_add_i32 s72, s73, s50
	global_load_lds_dwordx4 v[216:217], off
	v_lshl_add_u64 v[216:217], v[184:185], 0, s[22:23]
	s_mov_b32 m0, s72
	v_lshl_add_u64 v[184:185], v[184:185], 0, s[24:25]
	global_load_lds_dwordx4 v[216:217], off
	s_add_i32 m0, s72, 0x2000
	s_nop 0
	global_load_lds_dwordx4 v[184:185], off
	v_lshl_add_u64 v[184:185], s[46:47], 0, v[130:131]
	s_mov_b32 m0, s58
	s_nop 0
	global_load_lds_dwordx4 v[184:185], off
	v_lshl_add_u64 v[184:185], v[184:185], 0, s[10:11]
	s_mov_b32 m0, s59
	s_nop 0
	global_load_lds_dwordx4 v[184:185], off
	s_waitcnt vmcnt(8)
	s_waitcnt lgkmcnt(0)
	s_barrier
	s_setprio 1
	s_waitcnt lgkmcnt(0)
	v_mfma_f32_16x16x32_bf16 v[62:65], v[148:151], v[180:183], v[62:65]
	v_mfma_f32_16x16x32_bf16 v[62:65], v[152:155], v[188:191], v[62:65]
	v_mfma_f32_16x16x32_bf16 v[58:61], v[156:159], v[180:183], v[58:61]
	v_mfma_f32_16x16x32_bf16 v[58:61], v[160:163], v[188:191], v[58:61]
	v_mfma_f32_16x16x32_bf16 v[46:49], v[148:151], v[192:195], v[46:49]
	v_mfma_f32_16x16x32_bf16 v[46:49], v[152:155], v[196:199], v[46:49]
	v_mfma_f32_16x16x32_bf16 v[42:45], v[156:159], v[192:195], v[42:45]
	v_mfma_f32_16x16x32_bf16 v[42:45], v[160:163], v[196:199], v[42:45]
	v_mfma_f32_16x16x32_bf16 v[30:33], v[148:151], v[200:203], v[30:33]
	v_mfma_f32_16x16x32_bf16 v[30:33], v[152:155], v[204:207], v[30:33]
	v_mfma_f32_16x16x32_bf16 v[26:29], v[156:159], v[200:203], v[26:29]
	v_mfma_f32_16x16x32_bf16 v[26:29], v[160:163], v[204:207], v[26:29]
	v_mfma_f32_16x16x32_bf16 v[14:17], v[148:151], v[208:211], v[14:17]
	v_mfma_f32_16x16x32_bf16 v[14:17], v[152:155], v[212:215], v[14:17]
	v_mfma_f32_16x16x32_bf16 v[10:13], v[156:159], v[208:211], v[10:13]
	v_mfma_f32_16x16x32_bf16 v[10:13], v[160:163], v[212:215], v[10:13]
	s_setprio 0
	s_setprio 1
	v_mfma_f32_16x16x32_bf16 v[54:57], v[164:167], v[180:183], v[54:57]
	v_mfma_f32_16x16x32_bf16 v[54:57], v[168:171], v[188:191], v[54:57]
	v_mfma_f32_16x16x32_bf16 v[50:53], v[172:175], v[180:183], v[50:53]
	v_mfma_f32_16x16x32_bf16 v[50:53], v[176:179], v[188:191], v[50:53]
	v_mfma_f32_16x16x32_bf16 v[38:41], v[164:167], v[192:195], v[38:41]
	v_mfma_f32_16x16x32_bf16 v[38:41], v[168:171], v[196:199], v[38:41]
	v_mfma_f32_16x16x32_bf16 v[34:37], v[172:175], v[192:195], v[34:37]
	v_mfma_f32_16x16x32_bf16 v[34:37], v[176:179], v[196:199], v[34:37]
	v_mfma_f32_16x16x32_bf16 v[22:25], v[164:167], v[200:203], v[22:25]
	v_mfma_f32_16x16x32_bf16 v[22:25], v[168:171], v[204:207], v[22:25]
	v_mfma_f32_16x16x32_bf16 v[18:21], v[172:175], v[200:203], v[18:21]
	v_mfma_f32_16x16x32_bf16 v[18:21], v[176:179], v[204:207], v[18:21]
	v_mfma_f32_16x16x32_bf16 v[6:9], v[164:167], v[208:211], v[6:9]
	v_mfma_f32_16x16x32_bf16 v[6:9], v[168:171], v[212:215], v[6:9]
	v_mfma_f32_16x16x32_bf16 v[2:5], v[172:175], v[208:211], v[2:5]
	v_mfma_f32_16x16x32_bf16 v[2:5], v[176:179], v[212:215], v[2:5]
	s_setprio 0
	s_barrier
	s_add_i32 s71, s71, 2
	s_add_u32 s69, s69, 0x100
	s_addc_u32 s70, s70, 0
	s_add_u32 s44, s44, 0x10000
	s_addc_u32 s45, s45, 0
	s_cmp_gt_u32 s71, 61
	s_cbranch_scc0 .LBB0_1206
	s_lshl_b32 s29, s41, 2
	s_or_b32 s42, s29, s61
	s_ashr_i32 s41, s40, 31
	s_ashr_i32 s43, s42, 31
	s_lshl_b64 s[40:41], s[40:41], 16
	s_lshl_b64 s[42:43], s[42:43], 8
	s_add_u32 s40, s42, s40
	v_lshrrev_b32_e32 v142, 1, v147
	s_addc_u32 s41, s43, s41
	v_and_b32_e32 v150, 56, v142
	v_lshl_add_u64 v[142:143], s[40:41], 0, v[134:135]
	v_max_f32_e32 v122, v122, v122
	v_max_f32_e32 v123, v123, v123
	v_lshlrev_b64 v[142:143], 7, v[142:143]
	v_max_f32_e32 v122, 0, v122
	v_max_f32_e32 v123, 0, v123
	v_lshl_add_u64 v[148:149], s[16:17], 0, v[142:143]
	v_add_lshl_u32 v142, v150, s62, 1
	v_pk_mul_f32 v[150:151], v[122:123], v[122:123]
	v_max_f32_e32 v123, v124, v124
	v_max_f32_e32 v126, v126, v126
	v_max_f32_e32 v127, v127, v127
	v_max_f32_e32 v122, v128, v128
	v_max_f32_e32 v124, 0, v123
	v_max_f32_e32 v123, v129, v129
	v_max_f32_e32 v125, v125, v125
	v_max_f32_e32 v126, 0, v126
	v_max_f32_e32 v127, 0, v127
	v_max_f32_e32 v122, 0, v122
	v_max_f32_e32 v123, 0, v123
	v_max_f32_e32 v125, 0, v125
	v_mov_b32_e32 v143, v135
	v_pk_mul_f32 v[126:127], v[126:127], v[126:127]
	v_pk_mul_f32 v[128:129], v[122:123], v[122:123]
	v_pk_mul_f32 v[152:153], v[124:125], v[124:125]
	v_max_f32_e32 v114, v114, v114
	v_max_f32_e32 v115, v115, v115
	v_lshl_add_u64 v[148:149], v[148:149], 0, v[142:143]
	v_cvt_pk_bf16_f32 v122, v126, v127
	v_cvt_pk_bf16_f32 v123, v128, v129
	v_cvt_pk_bf16_f32 v124, v150, v151
	v_cvt_pk_bf16_f32 v125, v152, v153
	v_max_f32_e32 v114, 0, v114
	v_max_f32_e32 v115, 0, v115
	global_store_dwordx4 v[148:149], v[122:125], off nt
	v_max_f32_e32 v118, v118, v118
	v_max_f32_e32 v119, v119, v119
	v_pk_mul_f32 v[122:123], v[114:115], v[114:115]
	v_max_f32_e32 v115, v116, v116
	v_max_f32_e32 v118, 0, v118
	v_max_f32_e32 v119, 0, v119
	v_max_f32_e32 v114, v120, v120
	v_max_f32_e32 v116, 0, v115
	v_max_f32_e32 v115, v121, v121
	v_max_f32_e32 v117, v117, v117
	v_pk_mul_f32 v[118:119], v[118:119], v[118:119]
	v_max_f32_e32 v114, 0, v114
	v_max_f32_e32 v115, 0, v115
	v_max_f32_e32 v117, 0, v117
; __device__ __forceinline__ unsigned cvtpk(float lo, float hi) { f32x2 v = {lo, hi}; bf16x2_t b = __builtin_convertvector(v, bf16x2_t); return __builtin_bit_cast(unsigned, b); }
;     __device__ __forceinline__ void operator()(const Acc& acc, const Unit& u, int wr, int wc, int fr, int fq) const {
;     ...
;             for (int m = 0; m < 4; ++m) { bf16_t* rp = O + (((size_t)u.pm * (DFF / 64) + kt0) * 256 + (rl + ai * 128 + m * 16)) * 64 + cl;
; #pragma unroll
;                 for (int bj = 0; bj < 2; ++bj) { f32x4 v0 = acc[ai][bj][m][0], v1 = acc[ai][bj][m][1];
; #pragma unroll
;                     for (int e = 0; e < 4; ++e) { const float a = fmaxf(v0[e], 0.f), b = fmaxf(v1[e], 0.f); v0[e] = a * a; v1[e] = b * b; }
;                     u32x4 w; w.x = cvtpk(v0[0], v0[1]); w.y = cvtpk(v0[2], v0[3]); w.z = cvtpk(v1[0], v1[1]); w.w = cvtpk(v1[2], v1[3]);
;                     *(u32x4*)(rp + (size_t)bj * 2 * 256 * 64) = w; } }
	v_pk_mul_f32 v[120:121], v[114:115], v[114:115]
	v_pk_mul_f32 v[124:125], v[116:117], v[116:117]
	v_cvt_pk_bf16_f32 v114, v118, v119
	v_add_co_u32_e32 v118, vcc, s57, v148
	v_max_f32_e32 v106, v106, v106
	v_max_f32_e32 v107, v107, v107
	v_cvt_pk_bf16_f32 v115, v120, v121
	v_cvt_pk_bf16_f32 v116, v122, v123
	v_cvt_pk_bf16_f32 v117, v124, v125
	v_addc_co_u32_e32 v119, vcc, 0, v149, vcc
	v_max_f32_e32 v106, 0, v106
	v_max_f32_e32 v107, 0, v107
	global_store_dwordx4 v[118:119], v[114:117], off nt
	v_max_f32_e32 v110, v110, v110
	v_max_f32_e32 v111, v111, v111
	v_or_b32_e32 v114, 16, v134
	v_mov_b32_e32 v115, v135
	v_pk_mul_f32 v[116:117], v[106:107], v[106:107]
	v_max_f32_e32 v107, v108, v108
	v_lshl_add_u64 v[114:115], s[40:41], 0, v[114:115]
	v_max_f32_e32 v106, v112, v112
	v_max_f32_e32 v108, 0, v107
	v_max_f32_e32 v107, v113, v113
	v_max_f32_e32 v109, v109, v109
	v_lshlrev_b64 v[114:115], 7, v[114:115]
	v_max_f32_e32 v110, 0, v110
	v_max_f32_e32 v111, 0, v111
	v_max_f32_e32 v106, 0, v106
	v_max_f32_e32 v107, 0, v107
	v_max_f32_e32 v109, 0, v109
	v_lshl_add_u64 v[114:115], s[16:17], 0, v[114:115]
	v_pk_mul_f32 v[110:111], v[110:111], v[110:111]
	v_pk_mul_f32 v[112:113], v[106:107], v[106:107]
	v_pk_mul_f32 v[118:119], v[108:109], v[108:109]
	v_max_f32_e32 v98, v98, v98
	v_max_f32_e32 v99, v99, v99
	v_lshl_add_u64 v[114:115], v[114:115], 0, v[142:143]
	v_cvt_pk_bf16_f32 v106, v110, v111
	v_cvt_pk_bf16_f32 v107, v112, v113
	v_cvt_pk_bf16_f32 v108, v116, v117
	v_cvt_pk_bf16_f32 v109, v118, v119
	v_max_f32_e32 v98, 0, v98
	v_max_f32_e32 v99, 0, v99
	global_store_dwordx4 v[114:115], v[106:109], off nt
	v_max_f32_e32 v102, v102, v102
	v_max_f32_e32 v103, v103, v103
	v_pk_mul_f32 v[106:107], v[98:99], v[98:99]
	v_max_f32_e32 v99, v100, v100
	v_max_f32_e32 v102, 0, v102
	v_max_f32_e32 v103, 0, v103
	v_max_f32_e32 v98, v104, v104
	v_max_f32_e32 v100, 0, v99
	v_max_f32_e32 v99, v105, v105
	v_max_f32_e32 v101, v101, v101
	v_pk_mul_f32 v[102:103], v[102:103], v[102:103]
	v_max_f32_e32 v98, 0, v98
	v_max_f32_e32 v99, 0, v99
	v_max_f32_e32 v101, 0, v101
	v_pk_mul_f32 v[104:105], v[98:99], v[98:99]
	v_pk_mul_f32 v[108:109], v[100:101], v[100:101]
	v_cvt_pk_bf16_f32 v98, v102, v103
	v_add_co_u32_e32 v102, vcc, s57, v114
	v_max_f32_e32 v90, v90, v90
	v_max_f32_e32 v91, v91, v91
	v_cvt_pk_bf16_f32 v99, v104, v105
	v_cvt_pk_bf16_f32 v100, v106, v107
	v_cvt_pk_bf16_f32 v101, v108, v109
	v_addc_co_u32_e32 v103, vcc, 0, v115, vcc
	v_max_f32_e32 v90, 0, v90
	v_max_f32_e32 v91, 0, v91
	global_store_dwordx4 v[102:103], v[98:101], off nt
	v_max_f32_e32 v94, v94, v94
	v_max_f32_e32 v95, v95, v95
	v_or_b32_e32 v98, 32, v134
	v_mov_b32_e32 v99, v135
	v_pk_mul_f32 v[100:101], v[90:91], v[90:91]
	v_max_f32_e32 v91, v92, v92
	v_lshl_add_u64 v[98:99], s[40:41], 0, v[98:99]
	v_max_f32_e32 v90, v96, v96
	v_max_f32_e32 v92, 0, v91
	v_max_f32_e32 v91, v97, v97
	v_max_f32_e32 v93, v93, v93
	v_lshlrev_b64 v[98:99], 7, v[98:99]
	v_max_f32_e32 v94, 0, v94
	v_max_f32_e32 v95, 0, v95
	v_max_f32_e32 v90, 0, v90
	v_max_f32_e32 v91, 0, v91
	v_max_f32_e32 v93, 0, v93
	v_lshl_add_u64 v[98:99], s[16:17], 0, v[98:99]
	v_pk_mul_f32 v[94:95], v[94:95], v[94:95]
	v_pk_mul_f32 v[96:97], v[90:91], v[90:91]
	v_pk_mul_f32 v[102:103], v[92:93], v[92:93]
	v_max_f32_e32 v82, v82, v82
	v_max_f32_e32 v83, v83, v83
	v_lshl_add_u64 v[98:99], v[98:99], 0, v[142:143]
	v_cvt_pk_bf16_f32 v90, v94, v95
	v_cvt_pk_bf16_f32 v91, v96, v97
	v_cvt_pk_bf16_f32 v92, v100, v101
	v_cvt_pk_bf16_f32 v93, v102, v103
	v_max_f32_e32 v82, 0, v82
	v_max_f32_e32 v83, 0, v83
	global_store_dwordx4 v[98:99], v[90:93], off nt
	v_max_f32_e32 v86, v86, v86
	v_max_f32_e32 v87, v87, v87
	v_pk_mul_f32 v[90:91], v[82:83], v[82:83]
	v_max_f32_e32 v83, v84, v84
	v_max_f32_e32 v86, 0, v86
	v_max_f32_e32 v87, 0, v87
	v_max_f32_e32 v82, v88, v88
	v_max_f32_e32 v84, 0, v83
	v_max_f32_e32 v83, v89, v89
	v_max_f32_e32 v85, v85, v85
	v_pk_mul_f32 v[86:87], v[86:87], v[86:87]
	v_max_f32_e32 v82, 0, v82
	v_max_f32_e32 v83, 0, v83
	v_max_f32_e32 v85, 0, v85
	v_pk_mul_f32 v[88:89], v[82:83], v[82:83]
	v_pk_mul_f32 v[92:93], v[84:85], v[84:85]
	v_cvt_pk_bf16_f32 v82, v86, v87
	v_add_co_u32_e32 v86, vcc, s57, v98
	v_max_f32_e32 v74, v74, v74
	v_max_f32_e32 v75, v75, v75
	v_cvt_pk_bf16_f32 v83, v88, v89
	v_cvt_pk_bf16_f32 v84, v90, v91
	v_cvt_pk_bf16_f32 v85, v92, v93
	v_addc_co_u32_e32 v87, vcc, 0, v99, vcc
	v_max_f32_e32 v74, 0, v74
	v_max_f32_e32 v75, 0, v75
	global_store_dwordx4 v[86:87], v[82:85], off nt
	v_max_f32_e32 v78, v78, v78
	v_max_f32_e32 v79, v79, v79
	v_or_b32_e32 v82, 48, v134
	v_mov_b32_e32 v83, v135
	v_pk_mul_f32 v[84:85], v[74:75], v[74:75]
	v_max_f32_e32 v75, v76, v76
	v_lshl_add_u64 v[82:83], s[40:41], 0, v[82:83]
	v_max_f32_e32 v74, v80, v80
	v_max_f32_e32 v76, 0, v75
	v_max_f32_e32 v75, v81, v81
	v_max_f32_e32 v77, v77, v77
	v_lshlrev_b64 v[82:83], 7, v[82:83]
	v_max_f32_e32 v78, 0, v78
	v_max_f32_e32 v79, 0, v79
	v_max_f32_e32 v74, 0, v74
	v_max_f32_e32 v75, 0, v75
	v_max_f32_e32 v77, 0, v77
	v_lshl_add_u64 v[82:83], s[16:17], 0, v[82:83]
	v_pk_mul_f32 v[78:79], v[78:79], v[78:79]
	v_pk_mul_f32 v[80:81], v[74:75], v[74:75]
	v_pk_mul_f32 v[86:87], v[76:77], v[76:77]
	v_max_f32_e32 v66, v66, v66
	v_max_f32_e32 v67, v67, v67
	v_lshl_add_u64 v[82:83], v[82:83], 0, v[142:143]
	v_cvt_pk_bf16_f32 v74, v78, v79
	v_cvt_pk_bf16_f32 v75, v80, v81
	v_cvt_pk_bf16_f32 v76, v84, v85
	v_cvt_pk_bf16_f32 v77, v86, v87
	v_max_f32_e32 v66, 0, v66
	v_max_f32_e32 v67, 0, v67
	global_store_dwordx4 v[82:83], v[74:77], off nt
	v_max_f32_e32 v70, v70, v70
	v_max_f32_e32 v71, v71, v71
	v_pk_mul_f32 v[74:75], v[66:67], v[66:67]
	v_max_f32_e32 v67, v68, v68
; __device__ __forceinline__ unsigned cvtpk(float lo, float hi) { f32x2 v = {lo, hi}; bf16x2_t b = __builtin_convertvector(v, bf16x2_t); return __builtin_bit_cast(unsigned, b); }
;     __device__ __forceinline__ void operator()(const Acc& acc, const Unit& u, int wr, int wc, int fr, int fq) const {
;     ...
;             for (int m = 0; m < 4; ++m) { bf16_t* rp = O + (((size_t)u.pm * (DFF / 64) + kt0) * 256 + (rl + ai * 128 + m * 16)) * 64 + cl;
; #pragma unroll
;                 for (int bj = 0; bj < 2; ++bj) { f32x4 v0 = acc[ai][bj][m][0], v1 = acc[ai][bj][m][1];
; #pragma unroll
;                     for (int e = 0; e < 4; ++e) { const float a = fmaxf(v0[e], 0.f), b = fmaxf(v1[e], 0.f); v0[e] = a * a; v1[e] = b * b; }
;                     u32x4 w; w.x = cvtpk(v0[0], v0[1]); w.y = cvtpk(v0[2], v0[3]); w.z = cvtpk(v1[0], v1[1]); w.w = cvtpk(v1[2], v1[3]);
;                     *(u32x4*)(rp + (size_t)bj * 2 * 256 * 64) = w; } }
	v_max_f32_e32 v70, 0, v70
	v_max_f32_e32 v71, 0, v71
	v_max_f32_e32 v66, v72, v72
	v_max_f32_e32 v68, 0, v67
	v_max_f32_e32 v67, v73, v73
	v_max_f32_e32 v69, v69, v69
	v_pk_mul_f32 v[70:71], v[70:71], v[70:71]
	v_max_f32_e32 v66, 0, v66
	v_max_f32_e32 v67, 0, v67
	v_max_f32_e32 v69, 0, v69
	v_pk_mul_f32 v[72:73], v[66:67], v[66:67]
	v_pk_mul_f32 v[76:77], v[68:69], v[68:69]
	v_cvt_pk_bf16_f32 v66, v70, v71
	v_add_co_u32_e32 v70, vcc, s57, v82
	v_max_f32_e32 v58, v58, v58
	v_max_f32_e32 v59, v59, v59
	v_cvt_pk_bf16_f32 v67, v72, v73
	v_cvt_pk_bf16_f32 v68, v74, v75
	v_cvt_pk_bf16_f32 v69, v76, v77
	v_addc_co_u32_e32 v71, vcc, 0, v83, vcc
	v_max_f32_e32 v58, 0, v58
	v_max_f32_e32 v59, 0, v59
	global_store_dwordx4 v[70:71], v[66:69], off nt
	v_max_f32_e32 v62, v62, v62
	v_max_f32_e32 v63, v63, v63
	v_add_u32_e32 v66, 0x80, v134
	v_mov_b32_e32 v67, v135
	v_pk_mul_f32 v[68:69], v[58:59], v[58:59]
	v_max_f32_e32 v59, v60, v60
	v_lshl_add_u64 v[66:67], s[40:41], 0, v[66:67]
	v_max_f32_e32 v58, v64, v64
	v_max_f32_e32 v60, 0, v59
	v_max_f32_e32 v59, v65, v65
	v_max_f32_e32 v61, v61, v61
	v_lshlrev_b64 v[66:67], 7, v[66:67]
	v_max_f32_e32 v62, 0, v62
	v_max_f32_e32 v63, 0, v63
	v_max_f32_e32 v58, 0, v58
	v_max_f32_e32 v59, 0, v59
	v_max_f32_e32 v61, 0, v61
	v_lshl_add_u64 v[66:67], s[16:17], 0, v[66:67]
	v_pk_mul_f32 v[62:63], v[62:63], v[62:63]
	v_pk_mul_f32 v[64:65], v[58:59], v[58:59]
	v_pk_mul_f32 v[70:71], v[60:61], v[60:61]
	v_max_f32_e32 v50, v50, v50
	v_max_f32_e32 v51, v51, v51
	v_lshl_add_u64 v[66:67], v[66:67], 0, v[142:143]
	v_cvt_pk_bf16_f32 v58, v62, v63
	v_cvt_pk_bf16_f32 v59, v64, v65
	v_cvt_pk_bf16_f32 v60, v68, v69
	v_cvt_pk_bf16_f32 v61, v70, v71
	v_max_f32_e32 v50, 0, v50
	v_max_f32_e32 v51, 0, v51
	global_store_dwordx4 v[66:67], v[58:61], off nt
	v_max_f32_e32 v54, v54, v54
	v_max_f32_e32 v55, v55, v55
	v_pk_mul_f32 v[58:59], v[50:51], v[50:51]
	v_max_f32_e32 v51, v52, v52
	v_max_f32_e32 v54, 0, v54
	v_max_f32_e32 v55, 0, v55
	v_max_f32_e32 v50, v56, v56
	v_max_f32_e32 v52, 0, v51
	v_max_f32_e32 v51, v57, v57
	v_max_f32_e32 v53, v53, v53
	v_pk_mul_f32 v[54:55], v[54:55], v[54:55]
	v_max_f32_e32 v50, 0, v50
	v_max_f32_e32 v51, 0, v51
	v_max_f32_e32 v53, 0, v53
	v_pk_mul_f32 v[56:57], v[50:51], v[50:51]
	v_pk_mul_f32 v[60:61], v[52:53], v[52:53]
	v_cvt_pk_bf16_f32 v50, v54, v55
	v_add_co_u32_e32 v54, vcc, s57, v66
	v_max_f32_e32 v42, v42, v42
	v_max_f32_e32 v43, v43, v43
	v_cvt_pk_bf16_f32 v51, v56, v57
	v_cvt_pk_bf16_f32 v52, v58, v59
	v_cvt_pk_bf16_f32 v53, v60, v61
	v_addc_co_u32_e32 v55, vcc, 0, v67, vcc
	v_max_f32_e32 v42, 0, v42
	v_max_f32_e32 v43, 0, v43
	global_store_dwordx4 v[54:55], v[50:53], off nt
	v_max_f32_e32 v46, v46, v46
	v_max_f32_e32 v47, v47, v47
	v_add_u32_e32 v50, 0x90, v134
	v_mov_b32_e32 v51, v135
	v_pk_mul_f32 v[52:53], v[42:43], v[42:43]
	v_max_f32_e32 v43, v44, v44
	v_lshl_add_u64 v[50:51], s[40:41], 0, v[50:51]
	v_max_f32_e32 v42, v48, v48
	v_max_f32_e32 v44, 0, v43
	v_max_f32_e32 v43, v49, v49
	v_max_f32_e32 v45, v45, v45
	v_lshlrev_b64 v[50:51], 7, v[50:51]
	v_max_f32_e32 v46, 0, v46
	v_max_f32_e32 v47, 0, v47
	v_max_f32_e32 v42, 0, v42
	v_max_f32_e32 v43, 0, v43
	v_max_f32_e32 v45, 0, v45
	v_lshl_add_u64 v[50:51], s[16:17], 0, v[50:51]
	v_pk_mul_f32 v[46:47], v[46:47], v[46:47]
	v_pk_mul_f32 v[48:49], v[42:43], v[42:43]
	v_pk_mul_f32 v[54:55], v[44:45], v[44:45]
	v_max_f32_e32 v34, v34, v34
	v_max_f32_e32 v35, v35, v35
	v_lshl_add_u64 v[50:51], v[50:51], 0, v[142:143]
	v_cvt_pk_bf16_f32 v42, v46, v47
	v_cvt_pk_bf16_f32 v43, v48, v49
	v_cvt_pk_bf16_f32 v44, v52, v53
	v_cvt_pk_bf16_f32 v45, v54, v55
	v_max_f32_e32 v34, 0, v34
	v_max_f32_e32 v35, 0, v35
	global_store_dwordx4 v[50:51], v[42:45], off nt
	v_max_f32_e32 v38, v38, v38
	v_max_f32_e32 v39, v39, v39
	v_pk_mul_f32 v[42:43], v[34:35], v[34:35]
	v_max_f32_e32 v35, v36, v36
	v_max_f32_e32 v38, 0, v38
	v_max_f32_e32 v39, 0, v39
	v_max_f32_e32 v34, v40, v40
	v_max_f32_e32 v36, 0, v35
	v_max_f32_e32 v35, v41, v41
	v_max_f32_e32 v37, v37, v37
	v_pk_mul_f32 v[38:39], v[38:39], v[38:39]
	v_max_f32_e32 v34, 0, v34
	v_max_f32_e32 v35, 0, v35
	v_max_f32_e32 v37, 0, v37
	v_pk_mul_f32 v[40:41], v[34:35], v[34:35]
	v_pk_mul_f32 v[44:45], v[36:37], v[36:37]
	v_cvt_pk_bf16_f32 v34, v38, v39
; __device__ __forceinline__ unsigned cvtpk(float lo, float hi) { f32x2 v = {lo, hi}; bf16x2_t b = __builtin_convertvector(v, bf16x2_t); return __builtin_bit_cast(unsigned, b); }
; #define PG8_WAIT_V(n) asm volatile("s_waitcnt vmcnt(" #n ")" ::: "memory")
; #define PG8_BAR __builtin_amdgcn_s_barrier()
;     ...
;         cur = nxt; cA = nA; cB = nB; ++ui;
;         if constexpr (ALIGN) { if (wr == 1) PG8_BAR; }
;     }
;     PG8_WAIT_V(0);
;     if constexpr (!ALIGN) { if (wr == 0) PG8_BAR; }
;     PG8_BAR;
;     __device__ __forceinline__ void operator()(const Acc& acc, const Unit& u, int wr, int wc, int fr, int fq) const {
;     ...
;             for (int m = 0; m < 4; ++m) { bf16_t* rp = O + (((size_t)u.pm * (DFF / 64) + kt0) * 256 + (rl + ai * 128 + m * 16)) * 64 + cl;
; #pragma unroll
;                 for (int bj = 0; bj < 2; ++bj) { f32x4 v0 = acc[ai][bj][m][0], v1 = acc[ai][bj][m][1];
; #pragma unroll
;                     for (int e = 0; e < 4; ++e) { const float a = fmaxf(v0[e], 0.f), b = fmaxf(v1[e], 0.f); v0[e] = a * a; v1[e] = b * b; }
;                     u32x4 w; w.x = cvtpk(v0[0], v0[1]); w.y = cvtpk(v0[2], v0[3]); w.z = cvtpk(v1[0], v1[1]); w.w = cvtpk(v1[2], v1[3]);
;                     *(u32x4*)(rp + (size_t)bj * 2 * 256 * 64) = w; } }
	v_add_co_u32_e32 v38, vcc, s57, v50
	v_max_f32_e32 v26, v26, v26
	v_max_f32_e32 v27, v27, v27
	v_cvt_pk_bf16_f32 v35, v40, v41
	v_cvt_pk_bf16_f32 v36, v42, v43
	v_cvt_pk_bf16_f32 v37, v44, v45
	v_addc_co_u32_e32 v39, vcc, 0, v51, vcc
	v_max_f32_e32 v26, 0, v26
	v_max_f32_e32 v27, 0, v27
	global_store_dwordx4 v[38:39], v[34:37], off nt
	v_max_f32_e32 v30, v30, v30
	v_max_f32_e32 v31, v31, v31
	v_add_u32_e32 v34, 0xa0, v134
	v_mov_b32_e32 v35, v135
	v_pk_mul_f32 v[36:37], v[26:27], v[26:27]
	v_max_f32_e32 v27, v28, v28
	v_lshl_add_u64 v[34:35], s[40:41], 0, v[34:35]
	v_max_f32_e32 v26, v32, v32
	v_max_f32_e32 v28, 0, v27
	v_max_f32_e32 v27, v33, v33
	v_max_f32_e32 v29, v29, v29
	v_lshlrev_b64 v[34:35], 7, v[34:35]
	v_max_f32_e32 v30, 0, v30
	v_max_f32_e32 v31, 0, v31
	v_max_f32_e32 v26, 0, v26
	v_max_f32_e32 v27, 0, v27
	v_max_f32_e32 v29, 0, v29
	v_lshl_add_u64 v[34:35], s[16:17], 0, v[34:35]
	v_pk_mul_f32 v[30:31], v[30:31], v[30:31]
	v_pk_mul_f32 v[32:33], v[26:27], v[26:27]
	v_pk_mul_f32 v[38:39], v[28:29], v[28:29]
	v_max_f32_e32 v18, v18, v18
	v_max_f32_e32 v19, v19, v19
	v_lshl_add_u64 v[34:35], v[34:35], 0, v[142:143]
	v_cvt_pk_bf16_f32 v26, v30, v31
	v_cvt_pk_bf16_f32 v27, v32, v33
	v_cvt_pk_bf16_f32 v28, v36, v37
	v_cvt_pk_bf16_f32 v29, v38, v39
	v_max_f32_e32 v18, 0, v18
	v_max_f32_e32 v19, 0, v19
	global_store_dwordx4 v[34:35], v[26:29], off nt
	v_max_f32_e32 v22, v22, v22
	v_max_f32_e32 v23, v23, v23
	v_pk_mul_f32 v[26:27], v[18:19], v[18:19]
	v_max_f32_e32 v19, v20, v20
	v_max_f32_e32 v22, 0, v22
	v_max_f32_e32 v23, 0, v23
	v_max_f32_e32 v18, v24, v24
	v_max_f32_e32 v20, 0, v19
	v_max_f32_e32 v19, v25, v25
	v_max_f32_e32 v21, v21, v21
	v_pk_mul_f32 v[22:23], v[22:23], v[22:23]
	v_max_f32_e32 v18, 0, v18
	v_max_f32_e32 v19, 0, v19
	v_max_f32_e32 v21, 0, v21
	v_pk_mul_f32 v[24:25], v[18:19], v[18:19]
	v_pk_mul_f32 v[28:29], v[20:21], v[20:21]
	v_cvt_pk_bf16_f32 v18, v22, v23
	v_add_co_u32_e32 v22, vcc, s57, v34
	v_max_f32_e32 v10, v10, v10
	v_max_f32_e32 v11, v11, v11
	v_cvt_pk_bf16_f32 v19, v24, v25
	v_cvt_pk_bf16_f32 v20, v26, v27
	v_cvt_pk_bf16_f32 v21, v28, v29
	v_addc_co_u32_e32 v23, vcc, 0, v35, vcc
	v_max_f32_e32 v10, 0, v10
	v_max_f32_e32 v11, 0, v11
	global_store_dwordx4 v[22:23], v[18:21], off nt
	v_max_f32_e32 v14, v14, v14
	v_max_f32_e32 v15, v15, v15
	v_add_u32_e32 v18, 0xb0, v134
	v_mov_b32_e32 v19, v135
	v_pk_mul_f32 v[20:21], v[10:11], v[10:11]
	v_max_f32_e32 v11, v12, v12
	v_lshl_add_u64 v[18:19], s[40:41], 0, v[18:19]
	v_max_f32_e32 v10, v16, v16
	v_max_f32_e32 v12, 0, v11
	v_max_f32_e32 v11, v17, v17
	v_max_f32_e32 v13, v13, v13
	v_lshlrev_b64 v[18:19], 7, v[18:19]
	v_max_f32_e32 v14, 0, v14
	v_max_f32_e32 v15, 0, v15
	v_max_f32_e32 v10, 0, v10
	v_max_f32_e32 v11, 0, v11
	v_max_f32_e32 v13, 0, v13
	v_lshl_add_u64 v[18:19], s[16:17], 0, v[18:19]
	v_pk_mul_f32 v[14:15], v[14:15], v[14:15]
	v_pk_mul_f32 v[16:17], v[10:11], v[10:11]
	v_pk_mul_f32 v[22:23], v[12:13], v[12:13]
	v_max_f32_e32 v2, v2, v2
	v_max_f32_e32 v3, v3, v3
	v_lshl_add_u64 v[18:19], v[18:19], 0, v[142:143]
	v_cvt_pk_bf16_f32 v10, v14, v15
	v_cvt_pk_bf16_f32 v11, v16, v17
	v_cvt_pk_bf16_f32 v12, v20, v21
	v_cvt_pk_bf16_f32 v13, v22, v23
	v_max_f32_e32 v2, 0, v2
	v_max_f32_e32 v3, 0, v3
	global_store_dwordx4 v[18:19], v[10:13], off nt
	v_max_f32_e32 v6, v6, v6
	v_max_f32_e32 v7, v7, v7
	v_pk_mul_f32 v[10:11], v[2:3], v[2:3]
	v_max_f32_e32 v3, v4, v4
	v_max_f32_e32 v6, 0, v6
	v_max_f32_e32 v7, 0, v7
	v_max_f32_e32 v2, v8, v8
	v_max_f32_e32 v4, 0, v3
	v_max_f32_e32 v3, v9, v9
	v_pk_mul_f32 v[6:7], v[6:7], v[6:7]
	v_max_f32_e32 v2, 0, v2
	v_max_f32_e32 v3, 0, v3
	v_max_f32_e32 v5, v5, v5
	v_max_f32_e32 v5, 0, v5
	v_pk_mul_f32 v[8:9], v[2:3], v[2:3]
	v_cvt_pk_bf16_f32 v2, v6, v7
	v_add_co_u32_e32 v6, vcc, 0x10000, v18
	v_pk_mul_f32 v[12:13], v[4:5], v[4:5]
	s_nop 0
	v_addc_co_u32_e32 v7, vcc, 0, v19, vcc
	v_cvt_pk_bf16_f32 v3, v8, v9
	v_cvt_pk_bf16_f32 v4, v10, v11
	v_cvt_pk_bf16_f32 v5, v12, v13
	s_and_b64 vcc, exec, s[2:3]
	s_mov_b32 s41, s28
	s_mov_b32 s40, s34
	s_mov_b64 s[44:45], s[38:39]
	s_mov_b64 s[42:43], s[36:37]
	global_store_dwordx4 v[6:7], v[2:5], off nt
	s_cbranch_vccz .LBB0_1199
	s_waitcnt vmcnt(0)
	s_cmpk_gt_u32 s33, 0xff
	s_cbranch_scc1 .LBB0_1210
	s_barrier
